# speedup vs baseline: 1.0120x; 1.0120x over previous
; #define LAS __attribute__((address_space(3)))
; __device__ __forceinline__ void attn_blk(bool ctx_too, const bf16_t* U, bf16_t* Y, const float* nb_l, LAS unsigned char* lds, int lane, int wave, int tid) {
;     ...
;         if (!isc) { r = r0 + (wave >> 1); half = wave & 1; rs = min(max(r - 4, 0), 120); qrow0 = b * SEQ + r * 64 + 32 * half; } else qrow0 = ML + b * CTXL + 32 * wave;
;         bf16x8 qf[4];
;         { const bf16_t* qp = U + (size_t)(qrow0 + r32) * NU + UC_Q + 64 * h + 8 * hh;
; #pragma unroll
;           for (int kk = 0; kk < 4; ++kk) qf[kk] = *(const bf16x8*)(qp + 16 * kk); }
;         const int c = 32 * half + r32, cs = min(max(c - 8, 0), 48);
;         u32x4 kA, vA, kB, vB;
;         { const bf16_t* kv = U + (size_t)(ML + b * CTXL + srow) * NU + 64 * h + 8 * schunk; kA = *(const u32x4*)(kv + UC_K); vA = *(const u32x4*)(kv + UC_V);
;           kB = *(const u32x4*)(kv + (size_t)64 * NU + UC_K); vB = *(const u32x4*)(kv + (size_t)64 * NU + UC_V); }
;         *(LAS u32x4*)(lds + 16384 + kst_off) = kA; *(LAS u32x4*)(lds + 32768 + vst_off) = vA;
;         __syncthreads();
;         f32x16 o0, o1;
; #pragma unroll
;         for (int i = 0; i < 16; ++i) { o0[i] = 0.f; o1[i] = 0.f; }
;         float m = -1e30f, lsum = 0.f;
.LBB0_477:
	s_and_b32 s1, s1, 7
	v_add_u32_e32 v142, s26, v132
	v_mov_b64_e32 v[0:1], s[16:17]
	v_add_u32_e32 v3, s6, v180
	v_mad_i64_i32 v[4:5], s[4:5], v142, s50, v[0:1]
	s_lshl_b32 s46, s1, 7
	v_mad_i64_i32 v[0:1], s[4:5], v3, s50, v[0:1]
	v_lshl_add_u64 v[4:5], v[4:5], 0, s[46:47]
	v_mov_b32_e32 v139, v2
	v_lshl_add_u64 v[0:1], v[0:1], 0, s[46:47]
	v_mov_b32_e32 v141, v2
	v_lshl_add_u64 v[4:5], v[4:5], 0, v[138:139]
	v_lshl_add_u64 v[0:1], v[0:1], 0, v[140:141]
	global_load_dwordx4 v[100:103], v[4:5], off offset:1536
	global_load_dwordx4 v[104:107], v[4:5], off offset:1568
	global_load_dwordx4 v[108:111], v[4:5], off offset:1600
	global_load_dwordx4 v[112:115], v[4:5], off offset:1632
	global_load_dwordx4 v[116:119], v[0:1], off offset:2560
	global_load_dwordx4 v[120:123], v[0:1], off offset:3584
	v_add_co_u32_e32 v0, vcc, 0x48000, v0
	s_lshl_b32 s55, s1, 6
	s_nop 0
	v_addc_co_u32_e32 v1, vcc, 0, v1, vcc
	global_load_dwordx4 v[124:127], v[0:1], off offset:2560
	global_load_dwordx4 v[128:131], v[0:1], off offset:3584
	s_cmp_lt_i32 s43, 1
	s_waitcnt vmcnt(0) lgkmcnt(0)
	ds_write_b128 v193, v[116:119] offset:16384
	ds_write_b128 v194, v[120:123] offset:32768
	s_waitcnt lgkmcnt(0)
	s_barrier
	s_cbranch_scc1 .LBB0_463
	s_lshl_b32 s46, s55, 1
	v_lshl_add_u64 v[144:145], v[136:137], 0, s[46:47]
	s_lshl_b32 s0, s0, 13
	s_add_i32 s46, s6, 0x8080
	s_add_i32 s80, s54, 7
	s_cmp_lg_u32 s7, 0
	s_cselect_b64 s[4:5], -1, 0
	s_add_i32 s81, s6, 0x80c0
	s_lshl_b32 s6, s42, 6
	s_add_i32 s0, s0, s6
	s_sub_i32 s84, s0, 64
	s_mul_i32 s0, s1, 0x744
	s_add_i32 s1, s3, s42
	s_mulk_i32 s1, 0x7c
	v_mov_b32_e32 v14, v2
	v_mov_b32_e32 v15, v2
	s_add_i32 s0, s0, s1
	s_lshl_b32 s1, s7, 7
	v_mov_b32_e32 v0, v2
	v_mov_b32_e32 v1, v2
	v_mov_b32_e32 v3, v2
	v_mov_b32_e32 v4, v2
	v_mov_b32_e32 v5, v2
	v_mov_b32_e32 v6, v2
	v_mov_b32_e32 v7, v2
	v_mov_b32_e32 v8, v2
	v_mov_b32_e32 v9, v2
	v_mov_b32_e32 v10, v2
	v_mov_b32_e32 v11, v2
	v_mov_b32_e32 v12, v2
	v_mov_b32_e32 v13, v2
	v_mov_b64_e32 v[34:35], v[14:15]
	s_sub_i32 s0, s0, s1
	v_mov_b64_e32 v[32:33], v[12:13]
	v_mov_b64_e32 v[30:31], v[10:11]
	v_mov_b64_e32 v[28:29], v[8:9]
	v_mov_b64_e32 v[26:27], v[6:7]
	v_mov_b64_e32 v[24:25], v[4:5]
	v_mov_b64_e32 v[22:23], v[2:3]
	v_mov_b64_e32 v[20:21], v[0:1]
	v_mov_b64_e32 v[18:19], v[14:15]
	v_add_u32_e32 v139, s0, v192
	v_mov_b32_e32 v143, 0xf149f2ca
	v_mov_b32_e32 v141, 0
	s_mov_b32 s85, 3
	v_mov_b64_e32 v[16:17], v[12:13]
	v_mov_b64_e32 v[14:15], v[10:11]
	v_mov_b64_e32 v[12:13], v[8:9]
	v_mov_b64_e32 v[10:11], v[6:7]
	v_mov_b64_e32 v[8:9], v[4:5]
	v_mov_b64_e32 v[6:7], v[2:3]
	v_mov_b64_e32 v[4:5], v[0:1]
	s_branch .LBB0_481
